# plus workgroup stagger: WGs with odd (bid>>3) start the four f32-epilogue GEMM phases 12us late so the memory-bound epilogue bursts of the two halves de-phase
# baseline (speedup 1.0000x reference)
; #define LAS __attribute__((address_space(3)))
;     __device__ bool next(int i, Unit& u) const {
;         const long L = (long)i * G + c; if (L >= nwg) return false;
;         int wgid = (int)L; { const int q = nwg / NXCD, r = nwg % NXCD, xcd = wgid % NXCD, off = wgid / NXCD; wgid = (xcd < r ? xcd * (q + 1) : r * (q + 1) + (xcd - r) * q) + off; }
;         const int nig = WGM * nN, gid = wgid / nig, fm = gid * WGM, gsz = (nM - fm) < WGM ? (nM - fm) : WGM;
;         u.pm = fm + ((wgid % nig) % gsz); u.pn = (wgid % nig) / gsz; return true;
; __device__ __forceinline__ void xcd_barrier(unsigned* bar, volatile LAS unsigned* st, bool leader_thread) {
;     ...
;     __syncthreads();
; }
; __device__ __forceinline__ void* ldptr(ldsp lds, int idx) {
;     volatile LAS unsigned* t = (volatile LAS unsigned*)(lds + 143360) + 2 * idx;
;     const unsigned lo = __builtin_amdgcn_readfirstlane(t[0]), hi = __builtin_amdgcn_readfirstlane(t[1]);
;     return (void*)(((unsigned long long)hi << 32) | lo);
.LBB0_201:
	v_writelane_b32 v254, s58, 4
	s_nop 1
	v_writelane_b32 v254, s59, 5
	s_or_b64 exec, exec, s[2:3]
	s_bfe_u32 s98, s93, 0x10003
	s_cmp_eq_u32 s98, 0
	s_cbranch_scc1 .Lnostag0
	s_memrealtime s[100:101]
	s_waitcnt lgkmcnt(0)
	s_mov_b32 s99, s100
.Lstag0:
	s_sleep 20
	s_memrealtime s[100:101]
	s_waitcnt lgkmcnt(0)
	s_sub_u32 s100, s100, s99
	s_cmp_lt_u32 s100, 1200
	s_cbranch_scc1 .Lstag0
.Lnostag0:
	s_add_i32 s17, 0, 0x23090
	v_mov_b32_e32 v0, s17
	s_waitcnt lgkmcnt(0)
	s_barrier
	ds_read_b32 v0, v0
	s_add_i32 s0, 0, 0x23000
	v_mov_b32_e32 v1, s0
	s_add_i32 s0, 0, 0x23004
	s_add_i32 s42, 0, 0x23094
	v_mov_b32_e32 v2, s0
	s_add_i32 s0, 0, 0x23088
	s_waitcnt lgkmcnt(0)
	v_readfirstlane_b32 s8, v0
	v_mov_b32_e32 v0, s42
	v_mov_b32_e32 v3, s0
	s_add_i32 s0, 0, 0x2308c
	ds_read_b32 v0, v0
	v_mov_b32_e32 v4, s0
	ds_read_b32 v1, v1
	ds_read_b32 v2, v2
	ds_read_b32 v3, v3
	ds_read_b32 v4, v4
	s_waitcnt lgkmcnt(0)
	v_readfirstlane_b32 s9, v0
	v_mbcnt_lo_u32_b32 v8, -1, 0
	v_mbcnt_hi_u32_b32 v8, -1, v8
	s_cmpk_lt_i32 s93, 0x400
	v_or_b32_e32 v0, s59, v8
	v_readfirstlane_b32 s2, v1
	v_readfirstlane_b32 s3, v2
	v_readfirstlane_b32 s6, v3
	v_readfirstlane_b32 s7, v4
	s_cselect_b64 s[58:59], -1, 0
	s_cmpk_gt_i32 s93, 0x3ff
	v_readfirstlane_b32 s4, v0
	s_cbranch_scc1 .LBB0_229
	s_ashr_i32 s43, s93, 31
	s_lshr_b32 s0, s43, 29
	s_add_i32 s10, s93, s0
	s_and_b32 s0, s10, -8
	s_sub_i32 s11, s93, s0
	s_cmp_gt_i32 s11, -1
	s_cbranch_scc0 .LBB0_204
	s_lshl_b32 s5, s11, 7
	s_cbranch_execz .LBB0_205
	s_branch .LBB0_206

; __device__ __forceinline__ unsigned xb_ld(unsigned* p)              { return __hip_atomic_load(p, __ATOMIC_RELAXED, __HIP_MEMORY_SCOPE_AGENT); }
; __device__ __forceinline__ unsigned xb_add(unsigned* p, unsigned v) { return __hip_atomic_fetch_add(p, v, __ATOMIC_RELAXED, __HIP_MEMORY_SCOPE_AGENT); }
; __device__ __forceinline__ unsigned xb_xcc_id() { return (unsigned)__builtin_amdgcn_s_getreg((3 << 11) | 20) & 0xFu; }
; #define XB_SPIN(cond, bar) do { unsigned _sp = 0; while (cond) { __builtin_amdgcn_s_sleep(1); \
;     if ((++_sp & 255u) == 0u) { if (xb_ld(&(bar)[XB_TMO])) break; if (_sp > XB_SPIN_CAP) { atomicAdd(&(bar)[XB_TMO], 1u); break; } } } } while (0)
; __device__ __forceinline__ void xcd_barrier(unsigned* bar, volatile LAS unsigned* st, bool leader_thread) {
;     ...
;     if (leader_thread) {
;         const unsigned x = xb_xcc_id();
;         __builtin_amdgcn_s_waitcnt(0);
;         unsigned nloc = st[0], nx = st[1];
;         if (nloc == 0u) { xcd_barrier_complete(bar, x, nloc, nx); st[0] = nloc; st[1] = nx; }
;         const unsigned old = xb_add(&bar[XB_XSUB(x)], 1u);
;         const unsigned gen = old / nloc;
;         if (old + 1u == (gen + 1u) * nloc) {
;             __builtin_amdgcn_fence(__ATOMIC_RELEASE, "agent");
;             asm volatile("s_waitcnt vmcnt(0)" ::: "memory");
;             const unsigned og = xb_add(&bar[XB_TOP], 1u);
;             const unsigned tg = og / nx;
;             if (og + 1u == (tg + 1u) * nx) xb_add(&bar[XB_TOPGEN], 1u);
;             else XB_SPIN(xb_ld(&bar[XB_TOPGEN]) == tg, bar);
;             __builtin_amdgcn_fence(__ATOMIC_ACQUIRE, "agent");
;             xb_add(&bar[XB_XGEN(x)], 1u);
;             asm volatile("s_waitcnt vmcnt(0)" ::: "memory");
;         } else {
;             XB_SPIN(xb_ld(&bar[XB_XGEN(x)]) == gen, bar);
;             __builtin_amdgcn_fence(__ATOMIC_ACQUIRE, "agent");
;             asm volatile("s_waitcnt vmcnt(0)" ::: "memory");
;         }
;     }
;     __syncthreads();
.LBB0_764:
	s_or_b64 exec, exec, s[2:3]
	s_bfe_u32 s98, s93, 0x10003
	s_cmp_eq_u32 s98, 0
	s_cbranch_scc1 .Lnostag1
	s_memrealtime s[100:101]
	s_waitcnt lgkmcnt(0)
	s_mov_b32 s99, s100

; #define LAS __attribute__((address_space(3)))
;     __device__ bool next(int i, Unit& u) const {
;         const long L = (long)i * G + c; if (L >= nwg) return false;
;         int wgid = (int)L; { const int q = nwg / NXCD, r = nwg % NXCD, xcd = wgid % NXCD, off = wgid / NXCD; wgid = (xcd < r ? xcd * (q + 1) : r * (q + 1) + (xcd - r) * q) + off; }
;         const int nig = WGM * nN, gid = wgid / nig, fm = gid * WGM, gsz = (nM - fm) < WGM ? (nM - fm) : WGM;
;         u.pm = fm + ((wgid % nig) % gsz); u.pn = (wgid % nig) / gsz; return true;
; __device__ __forceinline__ void xcd_barrier(unsigned* bar, volatile LAS unsigned* st, bool leader_thread) {
;     ...
;     __syncthreads();
; }
; __device__ __forceinline__ void* ldptr(ldsp lds, int idx) {
;     volatile LAS unsigned* t = (volatile LAS unsigned*)(lds + 143360) + 2 * idx;
;     const unsigned lo = __builtin_amdgcn_readfirstlane(t[0]), hi = __builtin_amdgcn_readfirstlane(t[1]);
;     return (void*)(((unsigned long long)hi << 32) | lo);
.Lnostag1:
	s_add_i32 s13, 0, 0x23090
	s_add_i32 s0, 0, 0x23088
	v_mov_b32_e32 v0, s13
	s_add_i32 s46, 0, 0x23094
	v_mov_b32_e32 v2, s0
	s_add_i32 s0, 0, 0x2308c
	s_waitcnt lgkmcnt(0)
	s_barrier
	ds_read_b32 v0, v0
	v_mov_b32_e32 v1, s46
	v_mov_b32_e32 v3, s0
	ds_read_b32 v1, v1
	ds_read_b32 v2, v2
	ds_read_b32 v3, v3
	v_readlane_b32 s0, v254, 9
	s_waitcnt lgkmcnt(0)
	v_readfirstlane_b32 s6, v0
	v_mbcnt_lo_u32_b32 v8, -1, 0
	v_mbcnt_hi_u32_b32 v8, -1, v8
	v_readlane_b32 s1, v254, 10
	v_or_b32_e32 v0, s59, v8
	v_readfirstlane_b32 s7, v1
	v_readfirstlane_b32 s2, v2
	v_readfirstlane_b32 s3, v3
	s_and_b64 vcc, exec, s[0:1]
	v_readfirstlane_b32 s10, v0
	s_cbranch_vccnz .LBB0_788
	s_ashr_i32 s47, s93, 31
	s_lshr_b32 s0, s47, 29
	s_add_i32 s5, s93, s0
	s_and_b32 s0, s5, -8
	s_sub_i32 s8, s93, s0
	s_cmp_gt_i32 s8, -1
	s_cbranch_scc0 .LBB0_767
	s_lshl_b32 s4, s8, 7
	s_cbranch_execz .LBB0_768
	s_branch .LBB0_769

; #define LAS __attribute__((address_space(3)))
;     __device__ bool next(int i, Unit& u) const {
;         const long L = (long)i * G + c; if (L >= nwg) return false;
;         int wgid = (int)L; { const int q = nwg / NXCD, r = nwg % NXCD, xcd = wgid % NXCD, off = wgid / NXCD; wgid = (xcd < r ? xcd * (q + 1) : r * (q + 1) + (xcd - r) * q) + off; }
;         const int nig = WGM * nN, gid = wgid / nig, fm = gid * WGM, gsz = (nM - fm) < WGM ? (nM - fm) : WGM;
;         u.pm = fm + ((wgid % nig) % gsz); u.pn = (wgid % nig) / gsz; return true;
; __device__ __forceinline__ void xcd_barrier(unsigned* bar, volatile LAS unsigned* st, bool leader_thread) {
;     ...
;     __syncthreads();
; }
; __device__ __forceinline__ void* ldptr(ldsp lds, int idx) {
;     volatile LAS unsigned* t = (volatile LAS unsigned*)(lds + 143360) + 2 * idx;
;     const unsigned lo = __builtin_amdgcn_readfirstlane(t[0]), hi = __builtin_amdgcn_readfirstlane(t[1]);
;     return (void*)(((unsigned long long)hi << 32) | lo);
.Lnostag2:
	s_add_i32 s15, 0, 0x23090
	s_add_i32 s0, 0, 0x23088
	v_mov_b32_e32 v0, s15
	s_add_i32 s42, 0, 0x23094
	v_mov_b32_e32 v2, s0
	s_add_i32 s0, 0, 0x2308c
	s_waitcnt lgkmcnt(0)
	s_barrier
	ds_read_b32 v0, v0
	v_mov_b32_e32 v1, s42
	v_mov_b32_e32 v3, s0
	ds_read_b32 v1, v1
	ds_read_b32 v2, v2
	ds_read_b32 v3, v3
	v_readlane_b32 s0, v254, 9
	s_waitcnt lgkmcnt(0)
	v_readfirstlane_b32 s5, v0
	v_mbcnt_lo_u32_b32 v8, -1, 0
	v_mbcnt_hi_u32_b32 v8, -1, v8
	v_readlane_b32 s1, v254, 10
	v_or_b32_e32 v0, s59, v8
	v_readfirstlane_b32 s9, v1
	v_readfirstlane_b32 s2, v2
	v_readfirstlane_b32 s3, v3
	s_and_b64 vcc, exec, s[0:1]
	v_readfirstlane_b32 s4, v0
	s_cbranch_vccnz .LBB0_968
	s_ashr_i32 s43, s93, 31
	s_lshr_b32 s0, s43, 29
	s_add_i32 s7, s93, s0
	s_and_b32 s0, s7, -8
	s_sub_i32 s8, s93, s0
	s_cmp_gt_i32 s8, -1
	s_cbranch_scc0 .LBB0_943
	s_lshl_b32 s6, s8, 7
	s_cbranch_execz .LBB0_944
	s_branch .LBB0_945

; #define LAS __attribute__((address_space(3)))
;     __device__ bool next(int i, Unit& u) const {
;         const long L = (long)i * G + c; if (L >= nwg) return false;
;         int wgid = (int)L; { const int q = nwg / NXCD, r = nwg % NXCD, xcd = wgid % NXCD, off = wgid / NXCD; wgid = (xcd < r ? xcd * (q + 1) : r * (q + 1) + (xcd - r) * q) + off; }
;         const int nig = WGM * nN, gid = wgid / nig, fm = gid * WGM, gsz = (nM - fm) < WGM ? (nM - fm) : WGM;
;         u.pm = fm + ((wgid % nig) % gsz); u.pn = (wgid % nig) / gsz; return true;
; __device__ __forceinline__ void xcd_barrier(unsigned* bar, volatile LAS unsigned* st, bool leader_thread) {
;     ...
;     __syncthreads();
; }
; __device__ __forceinline__ void* ldptr(ldsp lds, int idx) {
;     volatile LAS unsigned* t = (volatile LAS unsigned*)(lds + 143360) + 2 * idx;
;     const unsigned lo = __builtin_amdgcn_readfirstlane(t[0]), hi = __builtin_amdgcn_readfirstlane(t[1]);
;     return (void*)(((unsigned long long)hi << 32) | lo);
.Lnostag3:
	s_add_i32 s15, 0, 0x23090
	s_add_i32 s0, 0, 0x23088
	v_mov_b32_e32 v0, s15
	s_add_i32 s48, 0, 0x23094
	v_mov_b32_e32 v2, s0
	s_add_i32 s0, 0, 0x2308c
	s_waitcnt lgkmcnt(0)
	s_barrier
	ds_read_b32 v0, v0
	v_mov_b32_e32 v1, s48
	v_mov_b32_e32 v3, s0
	ds_read_b32 v1, v1
	ds_read_b32 v2, v2
	ds_read_b32 v3, v3
	v_readlane_b32 s0, v254, 9
	s_waitcnt lgkmcnt(0)
	v_readfirstlane_b32 s8, v0
	v_mbcnt_lo_u32_b32 v8, -1, 0
	v_mbcnt_hi_u32_b32 v8, -1, v8
	v_readlane_b32 s1, v254, 10
	v_or_b32_e32 v0, s59, v8
	v_readfirstlane_b32 s9, v1
	v_readfirstlane_b32 s2, v2
	v_readfirstlane_b32 s3, v3
	s_and_b64 vcc, exec, s[0:1]
	v_readfirstlane_b32 s12, v0
	s_cbranch_vccnz .LBB0_1106
	s_ashr_i32 s49, s93, 31
	s_lshr_b32 s0, s49, 29
	s_add_i32 s5, s93, s0
	s_and_b32 s0, s5, -8
	s_sub_i32 s4, s93, s0
	s_cmp_gt_i32 s4, -1
	s_cbranch_scc0 .LBB0_1085
	s_lshl_b32 s6, s4, 7
	s_ashr_i32 s0, s5, 3
	s_cbranch_execz .LBB0_1086
	s_branch .LBB0_1087
